# rownorm x4 + finalnorm: nt (streaming) policy on the single-use f32 row loads
# speedup vs baseline: 1.0269x; 1.0269x over previous
.LBB0_49:
	v_lshrrev_b32_e32 v1, 3, v2
	v_and_b32_e32 v0, 0x700, v80
	v_and_b32_e32 v1, 0xf8, v1
	v_and_b32_e32 v3, 0xfffff807, v2
	v_or3_b32 v0, v0, v3, v1
	v_cndmask_b32_e32 v0, v2, v0, vcc
	v_ashrrev_i32_e32 v1, 31, v0
	v_lshlrev_b64 v[4:5], 12, v[0:1]
	v_lshl_add_u64 v[4:5], v[66:67], 0, v[4:5]
	s_waitcnt lgkmcnt(0)
	global_load_dwordx4 v[48:51], v[4:5], off nt
	global_load_dwordx4 v[52:55], v[4:5], off offset:1024 nt
	global_load_dwordx4 v[56:59], v[4:5], off offset:2048 nt
	global_load_dwordx4 v[60:63], v[4:5], off offset:3072 nt
	v_add_u32_e32 v3, s18, v2
	v_cmp_gt_i32_e64 s[6:7], s3, v3
	v_lshlrev_b64 v[0:1], 11, v[0:1]
	s_waitcnt vmcnt(1)
	v_mov_b32_e32 v84, v57
	v_cndmask_b32_e64 v4, v2, v3, s[6:7]
	v_lshlrev_b32_e32 v5, 5, v4
	v_lshrrev_b32_e32 v6, 3, v4
	v_and_b32_e32 v7, 0xfffff807, v4
	v_and_b32_e32 v5, 0x700, v5
	v_and_b32_e32 v6, 0xf8, v6
	v_or3_b32 v5, v5, v7, v6
	v_cndmask_b32_e32 v72, v4, v5, vcc
	v_ashrrev_i32_e32 v73, 31, v72
	v_lshlrev_b64 v[4:5], 12, v[72:73]
	v_lshl_add_u64 v[4:5], v[66:67], 0, v[4:5]
	global_load_dwordx4 v[16:19], v[4:5], off offset:1024 nt
	global_load_dwordx4 v[32:35], v[4:5], off nt
	global_load_dwordx4 v[20:23], v[4:5], off offset:2048 nt
	v_add_u32_e32 v3, s18, v3
	v_cmp_gt_i32_e64 s[8:9], s3, v3
	global_load_dwordx4 v[12:15], v[4:5], off offset:3072 nt
	v_add_u32_e32 v82, s18, v3
	v_cndmask_b32_e64 v4, v2, v3, s[8:9]
	v_lshlrev_b32_e32 v3, 5, v4
	v_lshrrev_b32_e32 v5, 3, v4
	v_cmp_gt_i32_e64 s[4:5], s3, v82
	v_and_b32_e32 v6, 0xfffff807, v4
	v_and_b32_e32 v3, 0x700, v3
	v_cndmask_b32_e64 v2, v2, v82, s[4:5]
	v_and_b32_e32 v5, 0xf8, v5
	v_lshlrev_b32_e32 v7, 5, v2
	v_lshrrev_b32_e32 v8, 3, v2
	v_or3_b32 v3, v3, v6, v5
	v_and_b32_e32 v9, 0xfffff807, v2
	v_and_b32_e32 v5, 0x700, v7
	v_and_b32_e32 v6, 0xf8, v8
	v_cndmask_b32_e32 v70, v4, v3, vcc
	v_or3_b32 v3, v5, v9, v6
	v_ashrrev_i32_e32 v71, 31, v70
	v_cndmask_b32_e32 v68, v2, v3, vcc
	v_lshlrev_b64 v[2:3], 12, v[70:71]
	v_mov_b32_e32 v8, v49
	v_mov_b32_e32 v9, v53
	v_lshl_add_u64 v[2:3], v[66:67], 0, v[2:3]
	v_mov_b32_e32 v6, v48
	v_mov_b32_e32 v7, v52
	s_waitcnt vmcnt(4)
	v_mov_b32_e32 v85, v61
	v_pk_mul_f32 v[8:9], v[8:9], v[8:9]
	global_load_dwordx4 v[44:47], v[2:3], off nt
	global_load_dwordx4 v[36:39], v[2:3], off offset:1024 nt
	global_load_dwordx4 v[40:43], v[2:3], off offset:2048 nt
	global_load_dwordx4 v[28:31], v[2:3], off offset:3072 nt
	v_mov_b32_e32 v2, v50
	v_mov_b32_e32 v3, v54
	v_mov_b32_e32 v26, v56
	v_mov_b32_e32 v27, v60
	v_pk_mul_f32 v[84:85], v[84:85], v[84:85]
	v_pk_fma_f32 v[6:7], v[6:7], v[6:7], v[8:9]
	v_mov_b32_e32 v4, v51
	v_mov_b32_e32 v5, v55
	v_mov_b32_e32 v10, v58
	v_mov_b32_e32 v11, v62
	v_pk_fma_f32 v[8:9], v[26:27], v[26:27], v[84:85]
	v_pk_fma_f32 v[2:3], v[2:3], v[2:3], v[6:7]
	v_mov_b32_e32 v24, v59
	v_mov_b32_e32 v25, v63
	v_pk_fma_f32 v[6:7], v[10:11], v[10:11], v[8:9]
	v_pk_fma_f32 v[2:3], v[4:5], v[4:5], v[2:3]
	v_pk_fma_f32 v[4:5], v[24:25], v[24:25], v[6:7]
	v_add_f32_e32 v2, v2, v3
	v_add_f32_e32 v2, v2, v4
	v_add_f32_e32 v8, v2, v5
	ds_bpermute_b32 v9, v74, v8
	v_ashrrev_i32_e32 v69, 31, v68
	v_lshlrev_b64 v[2:3], 12, v[68:69]
	v_lshl_add_u64 v[2:3], v[66:67], 0, v[2:3]
	global_load_dwordx4 v[4:7], v[2:3], off offset:1024 nt
	global_load_dwordx4 v[24:27], v[2:3], off nt
	s_waitcnt lgkmcnt(0)
	v_add_f32_e32 v8, v8, v9
	ds_bpermute_b32 v9, v75, v8
	v_lshl_add_u64 v[84:85], v[64:65], 0, v[0:1]
	s_waitcnt lgkmcnt(0)
	v_add_f32_e32 v83, v8, v9
	global_load_dwordx4 v[8:11], v[2:3], off offset:2048 nt
	s_nop 0
	global_load_dwordx4 v[0:3], v[2:3], off offset:3072 nt
	ds_bpermute_b32 v88, v76, v83
	s_waitcnt lgkmcnt(0)
	v_add_f32_e32 v83, v83, v88
	ds_bpermute_b32 v96, v77, v83
	s_waitcnt lgkmcnt(0)
	v_add_f32_e32 v83, v83, v96
	ds_bpermute_b32 v100, v78, v83
	s_waitcnt vmcnt(11)
	v_pk_mul_f32 v[86:87], v[16:17], v[16:17]
	s_waitcnt vmcnt(10)
	v_pk_mul_f32 v[90:91], v[32:33], v[32:33]
	v_add_f32_e32 v86, v86, v87
	v_add_f32_e32 v87, v90, v91
	s_waitcnt lgkmcnt(0)
	v_add_f32_e32 v83, v83, v100
	ds_bpermute_b32 v90, v79, v83
	v_pk_mul_f32 v[88:89], v[18:19], v[18:19]
	v_pk_mul_f32 v[92:93], v[34:35], v[34:35]
	v_add_f32_e32 v86, v86, v88
	s_waitcnt vmcnt(9)
	v_pk_mul_f32 v[94:95], v[20:21], v[20:21]
	s_waitcnt lgkmcnt(0)
	v_add_f32_e32 v83, v83, v90
	v_fmamk_f32 v83, v83, 0x3a800000, v81
	v_mul_f32_e32 v90, 0x4b800000, v83
	v_cmp_gt_f32_e64 s[10:11], s22, v83
	v_add_f32_e32 v87, v87, v92
	v_pk_mul_f32 v[96:97], v[22:23], v[22:23]
	v_cndmask_b32_e64 v83, v83, v90, s[10:11]
	v_rsq_f32_e32 v83, v83
	v_add_f32_e32 v90, v86, v89
	s_waitcnt vmcnt(8)
	v_pk_mul_f32 v[98:99], v[12:13], v[12:13]
	v_add_f32_e32 v91, v94, v95
	v_mul_f32_e32 v86, 0x45800000, v83
	v_cndmask_b32_e64 v86, v83, v86, s[10:11]
	v_pk_mul_f32 v[48:49], v[48:49], v[86:87] op_sel_hi:[1,0]
	v_pk_mul_f32 v[50:51], v[50:51], v[86:87] op_sel_hi:[1,0]
	v_add_f32_e32 v88, v91, v96
	v_add_f32_e32 v91, v87, v93
	v_pk_mul_f32 v[52:53], v[52:53], v[86:87] op_sel_hi:[1,0]
	v_pk_mul_f32 v[54:55], v[54:55], v[86:87] op_sel_hi:[1,0]
	v_pk_mul_f32 v[56:57], v[56:57], v[86:87] op_sel_hi:[1,0]
	v_pk_mul_f32 v[58:59], v[58:59], v[86:87] op_sel_hi:[1,0]
	v_pk_mul_f32 v[60:61], v[60:61], v[86:87] op_sel_hi:[1,0]
	v_pk_mul_f32 v[62:63], v[62:63], v[86:87] op_sel_hi:[1,0]
	v_cvt_pk_bf16_f32 v86, v48, v49
	v_cvt_pk_bf16_f32 v87, v50, v51
	v_add_f32_e32 v50, v98, v99
	v_pk_mul_f32 v[48:49], v[14:15], v[14:15]
	v_add_f32_e32 v92, v88, v97
	v_add_f32_e32 v48, v50, v48
	v_add_f32_e32 v50, v48, v49
	s_waitcnt vmcnt(6)
	v_pk_mul_f32 v[48:49], v[36:37], v[36:37]
	v_cvt_pk_bf16_f32 v88, v52, v53
	v_add_f32_e32 v51, v48, v49
	v_pk_mul_f32 v[48:49], v[38:39], v[38:39]
	v_cvt_pk_bf16_f32 v89, v54, v55
	v_add_f32_e32 v48, v51, v48
	v_add_f32_e32 v51, v48, v49
	v_pk_mul_f32 v[48:49], v[44:45], v[44:45]
	v_cvt_pk_bf16_f32 v54, v56, v57
	v_add_f32_e32 v52, v48, v49
	v_pk_mul_f32 v[48:49], v[46:47], v[46:47]
	v_cvt_pk_bf16_f32 v55, v58, v59
	v_add_f32_e32 v48, v52, v48
	v_add_f32_e32 v52, v48, v49
	s_waitcnt vmcnt(5)
	v_pk_mul_f32 v[48:49], v[40:41], v[40:41]
	s_nop 0
	v_add_f32_e32 v53, v48, v49
	v_pk_mul_f32 v[48:49], v[42:43], v[42:43]
	s_nop 0
	v_add_f32_e32 v48, v53, v48
	v_add_f32_e32 v53, v48, v49
	s_waitcnt vmcnt(4)
	v_pk_mul_f32 v[48:49], v[28:29], v[28:29]
	s_nop 0
	v_add_f32_e32 v56, v48, v49
	v_pk_mul_f32 v[48:49], v[30:31], v[30:31]
	s_nop 0
	v_add_f32_e32 v48, v56, v48
	v_add_f32_e32 v56, v48, v49
	s_waitcnt vmcnt(3)
	v_pk_mul_f32 v[48:49], v[4:5], v[4:5]
	s_nop 0
	v_add_f32_e32 v57, v48, v49
	v_pk_mul_f32 v[48:49], v[6:7], v[6:7]
	s_nop 0
	v_add_f32_e32 v48, v57, v48
	v_add_f32_e32 v57, v48, v49
	s_waitcnt vmcnt(2)
	v_pk_mul_f32 v[48:49], v[24:25], v[24:25]
	s_nop 0
	v_add_f32_e32 v58, v48, v49
	v_pk_mul_f32 v[48:49], v[26:27], v[26:27]
	s_nop 0
	v_add_f32_e32 v48, v58, v48
	v_add_f32_e32 v58, v48, v49
	s_waitcnt vmcnt(1)
	v_pk_mul_f32 v[48:49], v[8:9], v[8:9]
	s_nop 0
	v_add_f32_e32 v59, v48, v49
	v_pk_mul_f32 v[48:49], v[10:11], v[10:11]
	s_nop 0
	v_add_f32_e32 v48, v59, v48
	v_add_f32_e32 v59, v48, v49
	s_waitcnt vmcnt(0)
	v_pk_mul_f32 v[48:49], v[0:1], v[0:1]
	s_nop 0
	v_add_f32_e32 v83, v48, v49
	v_pk_mul_f32 v[48:49], v[2:3], v[2:3]
	s_nop 0
	v_add_f32_e32 v48, v83, v48
	v_add_f32_e32 v48, v48, v49
	v_add_f32_e32 v49, v91, v90
	v_add_f32_e32 v49, v49, v92
	v_add_f32_e32 v49, v49, v50
	v_add_f32_e32 v50, v52, v51
	v_add_f32_e32 v51, v58, v57
	v_add_f32_e32 v50, v50, v53
	v_add_f32_e32 v51, v51, v59
	v_add_f32_e32 v50, v50, v56
	v_add_f32_e32 v48, v51, v48
	ds_bpermute_b32 v52, v74, v49
	ds_bpermute_b32 v53, v74, v50
	ds_bpermute_b32 v51, v74, v48
	v_cvt_pk_bf16_f32 v56, v60, v61
	v_cvt_pk_bf16_f32 v57, v62, v63
	s_waitcnt lgkmcnt(2)
	v_add_f32_e32 v49, v49, v52
	s_waitcnt lgkmcnt(1)
	v_add_f32_e32 v50, v50, v53
	s_waitcnt lgkmcnt(0)
	v_add_f32_e32 v48, v48, v51
	ds_bpermute_b32 v52, v75, v49
	ds_bpermute_b32 v53, v75, v50
	ds_bpermute_b32 v51, v75, v48
	global_store_dwordx2 v[84:85], v[86:87], off
	global_store_dwordx2 v[84:85], v[88:89], off offset:512
	global_store_dwordx2 v[84:85], v[54:55], off offset:1024
	global_store_dwordx2 v[84:85], v[56:57], off offset:1536
	s_waitcnt lgkmcnt(2)
	v_add_f32_e32 v49, v49, v52
	s_waitcnt lgkmcnt(1)
	v_add_f32_e32 v50, v50, v53
	s_waitcnt lgkmcnt(0)
	v_add_f32_e32 v48, v48, v51
	ds_bpermute_b32 v52, v76, v49
	ds_bpermute_b32 v53, v76, v50
	ds_bpermute_b32 v51, v76, v48
	s_waitcnt lgkmcnt(2)
	v_add_f32_e32 v49, v49, v52
	s_waitcnt lgkmcnt(1)
	v_add_f32_e32 v50, v50, v53
	s_waitcnt lgkmcnt(0)
	v_add_f32_e32 v48, v48, v51
	ds_bpermute_b32 v52, v77, v49
	ds_bpermute_b32 v53, v77, v50
	ds_bpermute_b32 v51, v77, v48
	s_waitcnt lgkmcnt(2)
	v_add_f32_e32 v49, v49, v52
	s_waitcnt lgkmcnt(1)
	v_add_f32_e32 v50, v50, v53
	s_waitcnt lgkmcnt(0)
	v_add_f32_e32 v48, v48, v51
	ds_bpermute_b32 v52, v78, v49
	ds_bpermute_b32 v53, v78, v50
	ds_bpermute_b32 v51, v78, v48
	s_waitcnt lgkmcnt(2)
	v_add_f32_e32 v52, v49, v52
	s_waitcnt lgkmcnt(1)
	v_add_f32_e32 v50, v50, v53
	s_waitcnt lgkmcnt(0)
	v_add_f32_e32 v48, v48, v51
	ds_bpermute_b32 v53, v79, v52
	ds_bpermute_b32 v51, v79, v50
	ds_bpermute_b32 v49, v79, v48
	s_and_saveexec_b64 s[10:11], s[6:7]
	s_cbranch_execnz .LBB0_52
	s_or_b64 exec, exec, s[10:11]
	s_and_saveexec_b64 s[10:11], s[8:9]
	s_cbranch_execnz .LBB0_53

.LBB0_388:
	v_add_u32_e32 v0, s18, v58
	v_cmp_gt_i32_e64 s[8:9], s3, v0
	v_lshrrev_b32_e32 v69, 3, v58
	v_and_b32_e32 v59, 0x700, v66
	v_cndmask_b32_e64 v1, v58, v0, s[8:9]
	v_lshlrev_b32_e32 v2, 5, v1
	v_lshrrev_b32_e32 v3, 3, v1
	v_and_b32_e32 v2, 0x700, v2
	v_and_b32_e32 v3, 0xf8, v3
	v_and_b32_e32 v4, 0xfffff807, v1
	v_or3_b32 v2, v2, v4, v3
	v_cndmask_b32_e32 v56, v1, v2, vcc
	v_add_u32_e32 v2, s18, v0
	v_cmp_gt_i32_e64 s[4:5], s3, v2
	v_ashrrev_i32_e32 v57, 31, v56
	v_add_u32_e32 v68, s18, v2
	v_cndmask_b32_e64 v3, v58, v2, s[4:5]
	v_lshlrev_b32_e32 v0, 5, v3
	v_and_b32_e32 v4, 0x700, v0
	v_lshlrev_b64 v[0:1], 12, v[56:57]
	v_lshl_add_u64 v[0:1], v[50:51], 0, v[0:1]
	v_lshrrev_b32_e32 v5, 3, v3
	global_load_dwordx4 v[44:47], v[0:1], off nt
	global_load_dwordx4 v[40:43], v[0:1], off offset:1024 nt
	v_and_b32_e32 v5, 0xf8, v5
	v_and_b32_e32 v6, 0xfffff807, v3
	global_load_dwordx4 v[36:39], v[0:1], off offset:2048 nt
	global_load_dwordx4 v[32:35], v[0:1], off offset:3072 nt
	v_or3_b32 v0, v4, v6, v5
	v_cndmask_b32_e32 v54, v3, v0, vcc
	v_ashrrev_i32_e32 v55, 31, v54
	v_lshlrev_b64 v[0:1], 12, v[54:55]
	v_lshl_add_u64 v[0:1], v[50:51], 0, v[0:1]
	v_cmp_gt_i32_e64 s[6:7], s3, v68
	global_load_dwordx4 v[28:31], v[0:1], off nt
	global_load_dwordx4 v[24:27], v[0:1], off offset:1024 nt
	global_load_dwordx4 v[20:23], v[0:1], off offset:2048 nt
	global_load_dwordx4 v[16:19], v[0:1], off offset:3072 nt
	v_cndmask_b32_e64 v0, v58, v68, s[6:7]
	v_lshlrev_b32_e32 v1, 5, v0
	v_lshrrev_b32_e32 v2, 3, v0
	v_and_b32_e32 v3, 0xfffff807, v0
	v_and_b32_e32 v1, 0x700, v1
	v_and_b32_e32 v2, 0xf8, v2
	v_or3_b32 v1, v1, v3, v2
	v_cndmask_b32_e32 v52, v0, v1, vcc
	v_ashrrev_i32_e32 v53, 31, v52
	v_lshlrev_b64 v[0:1], 12, v[52:53]
	v_lshl_add_u64 v[0:1], v[50:51], 0, v[0:1]
	global_load_dwordx4 v[12:15], v[0:1], off nt
	global_load_dwordx4 v[8:11], v[0:1], off offset:1024 nt
	global_load_dwordx4 v[4:7], v[0:1], off offset:2048 nt
	s_nop 0
	global_load_dwordx4 v[0:3], v[0:1], off offset:3072 nt
	s_waitcnt lgkmcnt(0)
	v_and_b32_e32 v70, 0xfffff807, v58
	v_and_b32_e32 v69, 0xf8, v69
	v_or3_b32 v59, v59, v70, v69
	v_cndmask_b32_e32 v58, v58, v59, vcc
	v_ashrrev_i32_e32 v59, 31, v58
	v_lshlrev_b64 v[70:71], 12, v[58:59]
	v_lshl_add_u64 v[70:71], v[50:51], 0, v[70:71]
	global_load_dwordx4 v[76:79], v[70:71], off nt
	global_load_dwordx4 v[80:83], v[70:71], off offset:1024 nt
	global_load_dwordx4 v[84:87], v[70:71], off offset:2048 nt
	global_load_dwordx4 v[88:91], v[70:71], off offset:3072 nt
	v_lshlrev_b64 v[58:59], 11, v[58:59]
	v_lshl_add_u64 v[58:59], v[48:49], 0, v[58:59]
	s_waitcnt vmcnt(15)
	v_pk_mul_f32 v[70:71], v[44:45], v[44:45]
	s_waitcnt vmcnt(14)
	v_pk_mul_f32 v[74:75], v[40:41], v[40:41]
	v_pk_mul_f32 v[72:73], v[46:47], v[46:47]
	v_pk_mul_f32 v[92:93], v[42:43], v[42:43]
	s_waitcnt vmcnt(13)
	v_pk_mul_f32 v[94:95], v[36:37], v[36:37]
	v_add_f32_e32 v69, v74, v75
	v_add_f32_e32 v110, v70, v71
	v_pk_mul_f32 v[96:97], v[38:39], v[38:39]
	s_waitcnt vmcnt(12)
	v_pk_mul_f32 v[98:99], v[32:33], v[32:33]
	v_add_f32_e32 v111, v94, v95
	v_add_f32_e32 v69, v69, v92
	v_add_f32_e32 v72, v110, v72
	v_pk_mul_f32 v[100:101], v[34:35], v[34:35]
	v_add_f32_e32 v112, v98, v99
	v_add_f32_e32 v92, v111, v96
	v_add_f32_e32 v69, v69, v93
	v_add_f32_e32 v72, v72, v73
	v_add_f32_e32 v96, v112, v100
	v_add_f32_e32 v73, v92, v97
	v_add_f32_e32 v69, v72, v69
	v_add_f32_e32 v92, v96, v101
	v_add_f32_e32 v69, v69, v73
	s_waitcnt vmcnt(11)
	v_pk_mul_f32 v[70:71], v[28:29], v[28:29]
	s_waitcnt vmcnt(9)
	v_pk_mul_f32 v[102:103], v[20:21], v[20:21]
	v_add_f32_e32 v69, v69, v92
	v_add_f32_e32 v70, v70, v71
	v_add_f32_e32 v71, v102, v103
	ds_bpermute_b32 v103, v60, v69
	v_pk_mul_f32 v[74:75], v[30:31], v[30:31]
	v_pk_mul_f32 v[94:95], v[24:25], v[24:25]
	v_pk_mul_f32 v[98:99], v[26:27], v[26:27]
	v_add_f32_e32 v94, v94, v95
	v_add_f32_e32 v70, v70, v74
	v_pk_mul_f32 v[104:105], v[22:23], v[22:23]
	v_add_f32_e32 v72, v94, v98
	v_add_f32_e32 v70, v70, v75
	s_waitcnt vmcnt(6)
	v_pk_mul_f32 v[74:75], v[8:9], v[8:9]
	s_waitcnt lgkmcnt(0)
	v_add_f32_e32 v69, v69, v103
	v_add_f32_e32 v72, v72, v99
	v_add_f32_e32 v71, v71, v104
	v_add_f32_e32 v74, v74, v75
	ds_bpermute_b32 v75, v61, v69
	v_pk_mul_f32 v[106:107], v[16:17], v[16:17]
	v_add_f32_e32 v70, v70, v72
	v_add_f32_e32 v71, v71, v105
	v_pk_mul_f32 v[108:109], v[18:19], v[18:19]
	v_add_f32_e32 v70, v70, v71
	v_add_f32_e32 v71, v106, v107
	v_add_f32_e32 v71, v71, v108
	v_add_f32_e32 v71, v71, v109
	v_add_f32_e32 v102, v70, v71
	v_pk_mul_f32 v[70:71], v[12:13], v[12:13]
	s_waitcnt lgkmcnt(0)
	v_add_f32_e32 v69, v69, v75
	v_add_f32_e32 v70, v70, v71
	ds_bpermute_b32 v71, v62, v69
	v_pk_mul_f32 v[72:73], v[14:15], v[14:15]
	v_pk_mul_f32 v[92:93], v[10:11], v[10:11]
	s_waitcnt vmcnt(5)
	v_pk_mul_f32 v[94:95], v[4:5], v[4:5]
	v_pk_mul_f32 v[96:97], v[6:7], v[6:7]
	s_waitcnt lgkmcnt(0)
	v_add_f32_e32 v69, v69, v71
	v_add_f32_e32 v74, v74, v92
	v_add_f32_e32 v70, v70, v72
	v_add_f32_e32 v72, v94, v95
	ds_bpermute_b32 v71, v63, v69
	v_add_f32_e32 v74, v74, v93
	v_add_f32_e32 v70, v70, v73
	v_add_f32_e32 v72, v72, v96
	s_waitcnt vmcnt(4)
	v_pk_mul_f32 v[98:99], v[0:1], v[0:1]
	v_add_f32_e32 v70, v70, v74
	v_add_f32_e32 v72, v72, v97
	v_pk_mul_f32 v[100:101], v[2:3], v[2:3]
	v_add_f32_e32 v96, v70, v72
	v_add_f32_e32 v70, v98, v99
	s_waitcnt vmcnt(3)
	v_mov_b32_e32 v92, v77
	s_waitcnt vmcnt(2)
	v_mov_b32_e32 v93, v81
	v_add_f32_e32 v70, v70, v100
	v_mov_b32_e32 v74, v76
	v_mov_b32_e32 v75, v80
	v_pk_mul_f32 v[92:93], v[92:93], v[92:93]
	v_add_f32_e32 v97, v70, v101
	s_waitcnt lgkmcnt(0)
	v_add_f32_e32 v69, v69, v71
	v_mov_b32_e32 v70, v78
	v_mov_b32_e32 v71, v82
	v_pk_fma_f32 v[74:75], v[74:75], v[74:75], v[92:93]
	s_waitcnt vmcnt(1)
	v_mov_b32_e32 v94, v85
	s_waitcnt vmcnt(0)
	v_mov_b32_e32 v95, v89
	v_mov_b32_e32 v72, v79
	v_mov_b32_e32 v73, v83
	v_pk_fma_f32 v[70:71], v[70:71], v[70:71], v[74:75]
	v_mov_b32_e32 v92, v84
	v_mov_b32_e32 v93, v88
	v_pk_mul_f32 v[94:95], v[94:95], v[94:95]
	v_pk_fma_f32 v[70:71], v[72:73], v[72:73], v[70:71]
	v_mov_b32_e32 v72, v86
	v_mov_b32_e32 v73, v90
	v_pk_fma_f32 v[92:93], v[92:93], v[92:93], v[94:95]
	v_mov_b32_e32 v74, v87
	v_mov_b32_e32 v75, v91
	v_pk_fma_f32 v[72:73], v[72:73], v[72:73], v[92:93]
	v_add_f32_e32 v70, v70, v71
	v_pk_fma_f32 v[72:73], v[74:75], v[74:75], v[72:73]
	ds_bpermute_b32 v74, v60, v102
	v_add_f32_e32 v70, v70, v72
	v_add_f32_e32 v70, v70, v73
	ds_bpermute_b32 v71, v60, v70
	ds_bpermute_b32 v98, v64, v69
	s_waitcnt lgkmcnt(2)
	v_add_f32_e32 v74, v102, v74
	ds_bpermute_b32 v75, v61, v74
	v_add_f32_e32 v72, v96, v97
	s_waitcnt lgkmcnt(2)
	v_add_f32_e32 v70, v70, v71
	ds_bpermute_b32 v71, v61, v70
	s_waitcnt lgkmcnt(2)
	v_add_f32_e32 v73, v69, v98
	ds_bpermute_b32 v69, v60, v72
	s_waitcnt lgkmcnt(2)
	v_add_f32_e32 v74, v74, v75
	ds_bpermute_b32 v75, v62, v74
	s_waitcnt lgkmcnt(2)
	v_add_f32_e32 v70, v70, v71
	ds_bpermute_b32 v71, v62, v70
	s_waitcnt lgkmcnt(2)
	v_add_f32_e32 v69, v72, v69
	ds_bpermute_b32 v72, v61, v69
	s_waitcnt lgkmcnt(2)
	v_add_f32_e32 v74, v74, v75
	ds_bpermute_b32 v75, v63, v74
	s_waitcnt lgkmcnt(2)
	v_add_f32_e32 v70, v70, v71
	ds_bpermute_b32 v71, v63, v70
	s_waitcnt lgkmcnt(2)
	v_add_f32_e32 v69, v69, v72
	ds_bpermute_b32 v72, v62, v69
	s_waitcnt lgkmcnt(2)
	v_add_f32_e32 v75, v74, v75
	ds_bpermute_b32 v92, v64, v75
	s_waitcnt lgkmcnt(2)
	v_add_f32_e32 v70, v70, v71
	ds_bpermute_b32 v71, v64, v70
	s_waitcnt lgkmcnt(2)
	v_add_f32_e32 v69, v69, v72
	ds_bpermute_b32 v72, v63, v69
	ds_bpermute_b32 v74, v65, v73
	s_waitcnt lgkmcnt(2)
	v_add_f32_e32 v70, v70, v71
	ds_bpermute_b32 v94, v65, v70
	v_add_f32_e32 v71, v75, v92
	s_waitcnt lgkmcnt(2)
	v_add_f32_e32 v69, v69, v72
	ds_bpermute_b32 v93, v64, v69
	ds_bpermute_b32 v72, v65, v71
	s_waitcnt lgkmcnt(2)
	v_add_f32_e32 v70, v70, v94
	v_fmamk_f32 v70, v70, 0x3a800000, v67
	v_mul_f32_e32 v75, 0x4b800000, v70
	v_cmp_gt_f32_e64 s[10:11], s22, v70
	s_waitcnt lgkmcnt(1)
	v_add_f32_e32 v69, v69, v93
	v_cndmask_b32_e64 v70, v70, v75, s[10:11]
	v_rsq_f32_e32 v75, v70
	ds_bpermute_b32 v70, v65, v69
	v_mul_f32_e32 v92, 0x45800000, v75
	v_cndmask_b32_e64 v92, v75, v92, s[10:11]
	v_pk_mul_f32 v[76:77], v[76:77], v[92:93] op_sel_hi:[1,0]
	v_pk_mul_f32 v[78:79], v[78:79], v[92:93] op_sel_hi:[1,0]
	v_cvt_pk_bf16_f32 v76, v76, v77
	v_cvt_pk_bf16_f32 v77, v78, v79
	global_store_dwordx2 v[58:59], v[76:77], off sc1
	v_pk_mul_f32 v[76:77], v[80:81], v[92:93] op_sel_hi:[1,0]
	v_pk_mul_f32 v[78:79], v[82:83], v[92:93] op_sel_hi:[1,0]
	v_cvt_pk_bf16_f32 v76, v76, v77
	v_cvt_pk_bf16_f32 v77, v78, v79
	global_store_dwordx2 v[58:59], v[76:77], off offset:512 sc1
	v_pk_mul_f32 v[76:77], v[84:85], v[92:93] op_sel_hi:[1,0]
	v_pk_mul_f32 v[78:79], v[86:87], v[92:93] op_sel_hi:[1,0]
	v_cvt_pk_bf16_f32 v76, v76, v77
	v_cvt_pk_bf16_f32 v77, v78, v79
	global_store_dwordx2 v[58:59], v[76:77], off offset:1024 sc1
	v_pk_mul_f32 v[76:77], v[88:89], v[92:93] op_sel_hi:[1,0]
	v_pk_mul_f32 v[78:79], v[90:91], v[92:93] op_sel_hi:[1,0]
	v_cvt_pk_bf16_f32 v76, v76, v77
	v_cvt_pk_bf16_f32 v77, v78, v79
	global_store_dwordx2 v[58:59], v[76:77], off offset:1536 sc1
	s_and_saveexec_b64 s[10:11], s[8:9]
	s_cbranch_execnz .LBB0_391
	s_or_b64 exec, exec, s[10:11]
	s_and_saveexec_b64 s[8:9], s[4:5]
	s_cbranch_execnz .LBB0_392

.LBB0_868:
	v_add_u32_e32 v0, s16, v58
	v_cmp_gt_i32_e64 s[6:7], s3, v0
	v_lshrrev_b32_e32 v69, 3, v58
	v_and_b32_e32 v59, 0x700, v66
	v_cndmask_b32_e64 v1, v58, v0, s[6:7]
	v_lshlrev_b32_e32 v2, 5, v1
	v_lshrrev_b32_e32 v3, 3, v1
	v_and_b32_e32 v2, 0x700, v2
	v_and_b32_e32 v3, 0xf8, v3
	v_and_b32_e32 v4, 0xfffff807, v1
	v_or3_b32 v2, v2, v4, v3
	v_cndmask_b32_e32 v56, v1, v2, vcc
	v_add_u32_e32 v2, s16, v0
	v_cmp_gt_i32_e64 s[0:1], s3, v2
	v_ashrrev_i32_e32 v57, 31, v56
	v_add_u32_e32 v68, s16, v2
	v_cndmask_b32_e64 v3, v58, v2, s[0:1]
	v_lshlrev_b32_e32 v0, 5, v3
	v_and_b32_e32 v4, 0x700, v0
	v_lshlrev_b64 v[0:1], 12, v[56:57]
	v_lshl_add_u64 v[0:1], v[50:51], 0, v[0:1]
	v_lshrrev_b32_e32 v5, 3, v3
	global_load_dwordx4 v[44:47], v[0:1], off nt
	global_load_dwordx4 v[40:43], v[0:1], off offset:1024 nt
	v_and_b32_e32 v5, 0xf8, v5
	v_and_b32_e32 v6, 0xfffff807, v3
	global_load_dwordx4 v[36:39], v[0:1], off offset:2048 nt
	global_load_dwordx4 v[32:35], v[0:1], off offset:3072 nt
	v_or3_b32 v0, v4, v6, v5
	v_cndmask_b32_e32 v54, v3, v0, vcc
	v_ashrrev_i32_e32 v55, 31, v54
	v_lshlrev_b64 v[0:1], 12, v[54:55]
	v_lshl_add_u64 v[0:1], v[50:51], 0, v[0:1]
	v_cmp_gt_i32_e64 s[4:5], s3, v68
	global_load_dwordx4 v[28:31], v[0:1], off nt
	global_load_dwordx4 v[24:27], v[0:1], off offset:1024 nt
	global_load_dwordx4 v[20:23], v[0:1], off offset:2048 nt
	global_load_dwordx4 v[16:19], v[0:1], off offset:3072 nt
	v_cndmask_b32_e64 v0, v58, v68, s[4:5]
	v_lshlrev_b32_e32 v1, 5, v0
	v_lshrrev_b32_e32 v2, 3, v0
	v_and_b32_e32 v3, 0xfffff807, v0
	v_and_b32_e32 v1, 0x700, v1
	v_and_b32_e32 v2, 0xf8, v2
	v_or3_b32 v1, v1, v3, v2
	v_cndmask_b32_e32 v52, v0, v1, vcc
	v_ashrrev_i32_e32 v53, 31, v52
	v_lshlrev_b64 v[0:1], 12, v[52:53]
	v_lshl_add_u64 v[0:1], v[50:51], 0, v[0:1]
	global_load_dwordx4 v[12:15], v[0:1], off nt
	global_load_dwordx4 v[8:11], v[0:1], off offset:1024 nt
	global_load_dwordx4 v[4:7], v[0:1], off offset:2048 nt
	s_nop 0
	global_load_dwordx4 v[0:3], v[0:1], off offset:3072 nt
	s_waitcnt lgkmcnt(0)
	v_and_b32_e32 v70, 0xfffff807, v58
	v_and_b32_e32 v69, 0xf8, v69
	v_or3_b32 v59, v59, v70, v69
	v_cndmask_b32_e32 v58, v58, v59, vcc
	v_ashrrev_i32_e32 v59, 31, v58
	v_lshlrev_b64 v[70:71], 12, v[58:59]
	v_lshl_add_u64 v[70:71], v[50:51], 0, v[70:71]
	global_load_dwordx4 v[76:79], v[70:71], off nt
	global_load_dwordx4 v[80:83], v[70:71], off offset:1024 nt
	global_load_dwordx4 v[84:87], v[70:71], off offset:2048 nt
	global_load_dwordx4 v[88:91], v[70:71], off offset:3072 nt
	v_lshlrev_b64 v[58:59], 11, v[58:59]
	v_lshl_add_u64 v[58:59], v[48:49], 0, v[58:59]
	s_waitcnt vmcnt(15)
	v_pk_mul_f32 v[70:71], v[44:45], v[44:45]
	s_waitcnt vmcnt(14)
	v_pk_mul_f32 v[74:75], v[40:41], v[40:41]
	v_pk_mul_f32 v[72:73], v[46:47], v[46:47]
	v_pk_mul_f32 v[92:93], v[42:43], v[42:43]
	s_waitcnt vmcnt(13)
	v_pk_mul_f32 v[94:95], v[36:37], v[36:37]
	v_add_f32_e32 v69, v74, v75
	v_add_f32_e32 v110, v70, v71
	v_pk_mul_f32 v[96:97], v[38:39], v[38:39]
	s_waitcnt vmcnt(12)
	v_pk_mul_f32 v[98:99], v[32:33], v[32:33]
	v_add_f32_e32 v111, v94, v95
	v_add_f32_e32 v69, v69, v92
	v_add_f32_e32 v72, v110, v72
	v_pk_mul_f32 v[100:101], v[34:35], v[34:35]
	v_add_f32_e32 v112, v98, v99
	v_add_f32_e32 v92, v111, v96
	v_add_f32_e32 v69, v69, v93
	v_add_f32_e32 v72, v72, v73
	v_add_f32_e32 v96, v112, v100
	v_add_f32_e32 v73, v92, v97
	v_add_f32_e32 v69, v72, v69
	v_add_f32_e32 v92, v96, v101
	v_add_f32_e32 v69, v69, v73
	s_waitcnt vmcnt(11)
	v_pk_mul_f32 v[70:71], v[28:29], v[28:29]
	s_waitcnt vmcnt(9)
	v_pk_mul_f32 v[102:103], v[20:21], v[20:21]
	v_add_f32_e32 v69, v69, v92
	v_add_f32_e32 v70, v70, v71
	v_add_f32_e32 v71, v102, v103
	ds_bpermute_b32 v103, v60, v69
	v_pk_mul_f32 v[74:75], v[30:31], v[30:31]
	v_pk_mul_f32 v[94:95], v[24:25], v[24:25]
	v_pk_mul_f32 v[98:99], v[26:27], v[26:27]
	v_add_f32_e32 v94, v94, v95
	v_add_f32_e32 v70, v70, v74
	v_pk_mul_f32 v[104:105], v[22:23], v[22:23]
	v_add_f32_e32 v72, v94, v98
	v_add_f32_e32 v70, v70, v75
	s_waitcnt vmcnt(6)
	v_pk_mul_f32 v[74:75], v[8:9], v[8:9]
	s_waitcnt lgkmcnt(0)
	v_add_f32_e32 v69, v69, v103
	v_add_f32_e32 v72, v72, v99
	v_add_f32_e32 v71, v71, v104
	v_add_f32_e32 v74, v74, v75
	ds_bpermute_b32 v75, v61, v69
	v_pk_mul_f32 v[106:107], v[16:17], v[16:17]
	v_add_f32_e32 v70, v70, v72
	v_add_f32_e32 v71, v71, v105
	v_pk_mul_f32 v[108:109], v[18:19], v[18:19]
	v_add_f32_e32 v70, v70, v71
	v_add_f32_e32 v71, v106, v107
	v_add_f32_e32 v71, v71, v108
	v_add_f32_e32 v71, v71, v109
	v_add_f32_e32 v102, v70, v71
	v_pk_mul_f32 v[70:71], v[12:13], v[12:13]
	s_waitcnt lgkmcnt(0)
	v_add_f32_e32 v69, v69, v75
	v_add_f32_e32 v70, v70, v71
	ds_bpermute_b32 v71, v62, v69
	v_pk_mul_f32 v[72:73], v[14:15], v[14:15]
	v_pk_mul_f32 v[92:93], v[10:11], v[10:11]
	s_waitcnt vmcnt(5)
	v_pk_mul_f32 v[94:95], v[4:5], v[4:5]
	v_pk_mul_f32 v[96:97], v[6:7], v[6:7]
	s_waitcnt lgkmcnt(0)
	v_add_f32_e32 v69, v69, v71
	v_add_f32_e32 v74, v74, v92
	v_add_f32_e32 v70, v70, v72
	v_add_f32_e32 v72, v94, v95
	ds_bpermute_b32 v71, v63, v69
	v_add_f32_e32 v74, v74, v93
	v_add_f32_e32 v70, v70, v73
	v_add_f32_e32 v72, v72, v96
	s_waitcnt vmcnt(4)
	v_pk_mul_f32 v[98:99], v[0:1], v[0:1]
	v_add_f32_e32 v70, v70, v74
	v_add_f32_e32 v72, v72, v97
	v_pk_mul_f32 v[100:101], v[2:3], v[2:3]
	v_add_f32_e32 v96, v70, v72
	v_add_f32_e32 v70, v98, v99
	s_waitcnt vmcnt(3)
	v_mov_b32_e32 v92, v77
	s_waitcnt vmcnt(2)
	v_mov_b32_e32 v93, v81
	v_add_f32_e32 v70, v70, v100
	v_mov_b32_e32 v74, v76
	v_mov_b32_e32 v75, v80
	v_pk_mul_f32 v[92:93], v[92:93], v[92:93]
	v_add_f32_e32 v97, v70, v101
	s_waitcnt lgkmcnt(0)
	v_add_f32_e32 v69, v69, v71
	v_mov_b32_e32 v70, v78
	v_mov_b32_e32 v71, v82
	v_pk_fma_f32 v[74:75], v[74:75], v[74:75], v[92:93]
	s_waitcnt vmcnt(1)
	v_mov_b32_e32 v94, v85
	s_waitcnt vmcnt(0)
	v_mov_b32_e32 v95, v89
	v_mov_b32_e32 v72, v79
	v_mov_b32_e32 v73, v83
	v_pk_fma_f32 v[70:71], v[70:71], v[70:71], v[74:75]
	v_mov_b32_e32 v92, v84
	v_mov_b32_e32 v93, v88
	v_pk_mul_f32 v[94:95], v[94:95], v[94:95]
	v_pk_fma_f32 v[70:71], v[72:73], v[72:73], v[70:71]
	v_mov_b32_e32 v72, v86
	v_mov_b32_e32 v73, v90
	v_pk_fma_f32 v[92:93], v[92:93], v[92:93], v[94:95]
	v_mov_b32_e32 v74, v87
	v_mov_b32_e32 v75, v91
	v_pk_fma_f32 v[72:73], v[72:73], v[72:73], v[92:93]
	v_add_f32_e32 v70, v70, v71
	v_pk_fma_f32 v[72:73], v[74:75], v[74:75], v[72:73]
	ds_bpermute_b32 v74, v60, v102
	v_add_f32_e32 v70, v70, v72
	v_add_f32_e32 v70, v70, v73
	ds_bpermute_b32 v71, v60, v70
	ds_bpermute_b32 v98, v64, v69
	s_waitcnt lgkmcnt(2)
	v_add_f32_e32 v74, v102, v74
	ds_bpermute_b32 v75, v61, v74
	v_add_f32_e32 v72, v96, v97
	s_waitcnt lgkmcnt(2)
	v_add_f32_e32 v70, v70, v71
	ds_bpermute_b32 v71, v61, v70
	s_waitcnt lgkmcnt(2)
	v_add_f32_e32 v73, v69, v98
	ds_bpermute_b32 v69, v60, v72
	s_waitcnt lgkmcnt(2)
	v_add_f32_e32 v74, v74, v75
	ds_bpermute_b32 v75, v62, v74
	s_waitcnt lgkmcnt(2)
	v_add_f32_e32 v70, v70, v71
	ds_bpermute_b32 v71, v62, v70
	s_waitcnt lgkmcnt(2)
	v_add_f32_e32 v69, v72, v69
	ds_bpermute_b32 v72, v61, v69
	s_waitcnt lgkmcnt(2)
	v_add_f32_e32 v74, v74, v75
	ds_bpermute_b32 v75, v63, v74
	s_waitcnt lgkmcnt(2)
	v_add_f32_e32 v70, v70, v71
	ds_bpermute_b32 v71, v63, v70
	s_waitcnt lgkmcnt(2)
	v_add_f32_e32 v69, v69, v72
	ds_bpermute_b32 v72, v62, v69
	s_waitcnt lgkmcnt(2)
	v_add_f32_e32 v75, v74, v75
	ds_bpermute_b32 v92, v64, v75
	s_waitcnt lgkmcnt(2)
	v_add_f32_e32 v70, v70, v71
	ds_bpermute_b32 v71, v64, v70
	s_waitcnt lgkmcnt(2)
	v_add_f32_e32 v69, v69, v72
	ds_bpermute_b32 v72, v63, v69
	ds_bpermute_b32 v74, v65, v73
	s_waitcnt lgkmcnt(2)
	v_add_f32_e32 v70, v70, v71
	ds_bpermute_b32 v94, v65, v70
	v_add_f32_e32 v71, v75, v92
	s_waitcnt lgkmcnt(2)
	v_add_f32_e32 v69, v69, v72
	ds_bpermute_b32 v93, v64, v69
	ds_bpermute_b32 v72, v65, v71
	s_waitcnt lgkmcnt(2)
	v_add_f32_e32 v70, v70, v94
	v_fmamk_f32 v70, v70, 0x3a800000, v67
	v_mul_f32_e32 v75, 0x4b800000, v70
	v_cmp_gt_f32_e64 s[8:9], s18, v70
	s_waitcnt lgkmcnt(1)
	v_add_f32_e32 v69, v69, v93
	v_cndmask_b32_e64 v70, v70, v75, s[8:9]
	v_rsq_f32_e32 v75, v70
	ds_bpermute_b32 v70, v65, v69
	v_mul_f32_e32 v92, 0x45800000, v75
	v_cndmask_b32_e64 v92, v75, v92, s[8:9]
	v_pk_mul_f32 v[76:77], v[76:77], v[92:93] op_sel_hi:[1,0]
	v_pk_mul_f32 v[78:79], v[78:79], v[92:93] op_sel_hi:[1,0]
	v_cvt_pk_bf16_f32 v76, v76, v77
	v_cvt_pk_bf16_f32 v77, v78, v79
	global_store_dwordx2 v[58:59], v[76:77], off sc1
	v_pk_mul_f32 v[76:77], v[80:81], v[92:93] op_sel_hi:[1,0]
	v_pk_mul_f32 v[78:79], v[82:83], v[92:93] op_sel_hi:[1,0]
	v_cvt_pk_bf16_f32 v76, v76, v77
	v_cvt_pk_bf16_f32 v77, v78, v79
	global_store_dwordx2 v[58:59], v[76:77], off offset:512 sc1
	v_pk_mul_f32 v[76:77], v[84:85], v[92:93] op_sel_hi:[1,0]
	v_pk_mul_f32 v[78:79], v[86:87], v[92:93] op_sel_hi:[1,0]
	v_cvt_pk_bf16_f32 v76, v76, v77
	v_cvt_pk_bf16_f32 v77, v78, v79
	global_store_dwordx2 v[58:59], v[76:77], off offset:1024 sc1
	v_pk_mul_f32 v[76:77], v[88:89], v[92:93] op_sel_hi:[1,0]
	v_pk_mul_f32 v[78:79], v[90:91], v[92:93] op_sel_hi:[1,0]
	v_cvt_pk_bf16_f32 v76, v76, v77
	v_cvt_pk_bf16_f32 v77, v78, v79
	global_store_dwordx2 v[58:59], v[76:77], off offset:1536 sc1
	s_and_saveexec_b64 s[8:9], s[6:7]
	s_cbranch_execnz .LBB0_871
	s_or_b64 exec, exec, s[8:9]
	s_and_saveexec_b64 s[6:7], s[0:1]
	s_cbranch_execnz .LBB0_872

.LBB0_1423:
	v_add_u32_e32 v0, s16, v58
	v_cmp_gt_i32_e64 s[6:7], s3, v0
	v_lshrrev_b32_e32 v69, 3, v58
	v_and_b32_e32 v59, 0x700, v66
	v_cndmask_b32_e64 v1, v58, v0, s[6:7]
	v_lshlrev_b32_e32 v2, 5, v1
	v_lshrrev_b32_e32 v3, 3, v1
	v_and_b32_e32 v2, 0x700, v2
	v_and_b32_e32 v3, 0xf8, v3
	v_and_b32_e32 v4, 0xfffff807, v1
	v_or3_b32 v2, v2, v4, v3
	v_cndmask_b32_e32 v56, v1, v2, vcc
	v_add_u32_e32 v2, s16, v0
	v_cmp_gt_i32_e64 s[0:1], s3, v2
	v_ashrrev_i32_e32 v57, 31, v56
	v_add_u32_e32 v68, s16, v2
	v_cndmask_b32_e64 v3, v58, v2, s[0:1]
	v_lshlrev_b32_e32 v0, 5, v3
	v_and_b32_e32 v4, 0x700, v0
	v_lshlrev_b64 v[0:1], 12, v[56:57]
	v_lshl_add_u64 v[0:1], v[50:51], 0, v[0:1]
	v_lshrrev_b32_e32 v5, 3, v3
	global_load_dwordx4 v[44:47], v[0:1], off nt
	global_load_dwordx4 v[40:43], v[0:1], off offset:1024 nt
	v_and_b32_e32 v5, 0xf8, v5
	v_and_b32_e32 v6, 0xfffff807, v3
	global_load_dwordx4 v[36:39], v[0:1], off offset:2048 nt
	global_load_dwordx4 v[32:35], v[0:1], off offset:3072 nt
	v_or3_b32 v0, v4, v6, v5
	v_cndmask_b32_e32 v54, v3, v0, vcc
	v_ashrrev_i32_e32 v55, 31, v54
	v_lshlrev_b64 v[0:1], 12, v[54:55]
	v_lshl_add_u64 v[0:1], v[50:51], 0, v[0:1]
	v_cmp_gt_i32_e64 s[4:5], s3, v68
	global_load_dwordx4 v[28:31], v[0:1], off nt
	global_load_dwordx4 v[24:27], v[0:1], off offset:1024 nt
	global_load_dwordx4 v[20:23], v[0:1], off offset:2048 nt
	global_load_dwordx4 v[16:19], v[0:1], off offset:3072 nt
	v_cndmask_b32_e64 v0, v58, v68, s[4:5]
	v_lshlrev_b32_e32 v1, 5, v0
	v_lshrrev_b32_e32 v2, 3, v0
	v_and_b32_e32 v3, 0xfffff807, v0
	v_and_b32_e32 v1, 0x700, v1
	v_and_b32_e32 v2, 0xf8, v2
	v_or3_b32 v1, v1, v3, v2
	v_cndmask_b32_e32 v52, v0, v1, vcc
	v_ashrrev_i32_e32 v53, 31, v52
	v_lshlrev_b64 v[0:1], 12, v[52:53]
	s_waitcnt lgkmcnt(0)
	v_lshl_add_u64 v[70:71], v[50:51], 0, v[0:1]
	global_load_dwordx4 v[12:15], v[70:71], off nt
	global_load_dwordx4 v[8:11], v[70:71], off offset:1024 nt
	global_load_dwordx4 v[4:7], v[70:71], off offset:2048 nt
	global_load_dwordx4 v[0:3], v[70:71], off offset:3072 nt
	v_and_b32_e32 v70, 0xfffff807, v58
	v_and_b32_e32 v69, 0xf8, v69
	v_or3_b32 v59, v59, v70, v69
	v_cndmask_b32_e32 v58, v58, v59, vcc
	v_ashrrev_i32_e32 v59, 31, v58
	v_lshlrev_b64 v[70:71], 12, v[58:59]
	v_lshl_add_u64 v[70:71], v[50:51], 0, v[70:71]
	global_load_dwordx4 v[76:79], v[70:71], off nt
	global_load_dwordx4 v[80:83], v[70:71], off offset:1024 nt
	global_load_dwordx4 v[84:87], v[70:71], off offset:2048 nt
	global_load_dwordx4 v[88:91], v[70:71], off offset:3072 nt
	v_lshlrev_b64 v[58:59], 11, v[58:59]
	v_lshl_add_u64 v[58:59], v[48:49], 0, v[58:59]
	s_waitcnt vmcnt(15)
	v_pk_mul_f32 v[70:71], v[44:45], v[44:45]
	s_waitcnt vmcnt(14)
	v_pk_mul_f32 v[74:75], v[40:41], v[40:41]
	v_pk_mul_f32 v[72:73], v[46:47], v[46:47]
	v_pk_mul_f32 v[92:93], v[42:43], v[42:43]
	s_waitcnt vmcnt(13)
	v_pk_mul_f32 v[94:95], v[36:37], v[36:37]
	v_add_f32_e32 v69, v74, v75
	v_add_f32_e32 v110, v70, v71
	v_pk_mul_f32 v[96:97], v[38:39], v[38:39]
	s_waitcnt vmcnt(12)
	v_pk_mul_f32 v[98:99], v[32:33], v[32:33]
	v_add_f32_e32 v111, v94, v95
	v_add_f32_e32 v69, v69, v92
	v_add_f32_e32 v72, v110, v72
	v_pk_mul_f32 v[100:101], v[34:35], v[34:35]
	v_add_f32_e32 v112, v98, v99
	v_add_f32_e32 v92, v111, v96
	v_add_f32_e32 v69, v69, v93
	v_add_f32_e32 v72, v72, v73
	v_add_f32_e32 v96, v112, v100
	v_add_f32_e32 v73, v92, v97
	v_add_f32_e32 v69, v72, v69
	v_add_f32_e32 v92, v96, v101
	v_add_f32_e32 v69, v69, v73
	s_waitcnt vmcnt(11)
	v_pk_mul_f32 v[70:71], v[28:29], v[28:29]
	s_waitcnt vmcnt(9)
	v_pk_mul_f32 v[102:103], v[20:21], v[20:21]
	v_add_f32_e32 v69, v69, v92
	v_add_f32_e32 v70, v70, v71
	v_add_f32_e32 v71, v102, v103
	ds_bpermute_b32 v103, v60, v69
	v_pk_mul_f32 v[74:75], v[30:31], v[30:31]
	v_pk_mul_f32 v[94:95], v[24:25], v[24:25]
	v_pk_mul_f32 v[98:99], v[26:27], v[26:27]
	v_add_f32_e32 v94, v94, v95
	v_add_f32_e32 v70, v70, v74
	v_pk_mul_f32 v[104:105], v[22:23], v[22:23]
	v_add_f32_e32 v72, v94, v98
	v_add_f32_e32 v70, v70, v75
	s_waitcnt vmcnt(6)
	v_pk_mul_f32 v[74:75], v[8:9], v[8:9]
	s_waitcnt lgkmcnt(0)
	v_add_f32_e32 v69, v69, v103
	v_add_f32_e32 v72, v72, v99
	v_add_f32_e32 v71, v71, v104
	v_add_f32_e32 v74, v74, v75
	ds_bpermute_b32 v75, v61, v69
	v_pk_mul_f32 v[106:107], v[16:17], v[16:17]
	v_add_f32_e32 v70, v70, v72
	v_add_f32_e32 v71, v71, v105
	v_pk_mul_f32 v[108:109], v[18:19], v[18:19]
	v_add_f32_e32 v70, v70, v71
	v_add_f32_e32 v71, v106, v107
	v_add_f32_e32 v71, v71, v108
	v_add_f32_e32 v71, v71, v109
	v_add_f32_e32 v102, v70, v71
	v_pk_mul_f32 v[70:71], v[12:13], v[12:13]
	s_waitcnt lgkmcnt(0)
	v_add_f32_e32 v69, v69, v75
	v_add_f32_e32 v70, v70, v71
	ds_bpermute_b32 v71, v62, v69
	v_pk_mul_f32 v[72:73], v[14:15], v[14:15]
	v_pk_mul_f32 v[92:93], v[10:11], v[10:11]
	s_waitcnt vmcnt(5)
	v_pk_mul_f32 v[94:95], v[4:5], v[4:5]
	v_pk_mul_f32 v[96:97], v[6:7], v[6:7]
	s_waitcnt lgkmcnt(0)
	v_add_f32_e32 v69, v69, v71
	v_add_f32_e32 v74, v74, v92
	v_add_f32_e32 v70, v70, v72
	v_add_f32_e32 v72, v94, v95
	ds_bpermute_b32 v71, v63, v69
	v_add_f32_e32 v74, v74, v93
	v_add_f32_e32 v70, v70, v73
	v_add_f32_e32 v72, v72, v96
	s_waitcnt vmcnt(4)
	v_pk_mul_f32 v[98:99], v[0:1], v[0:1]
	v_add_f32_e32 v70, v70, v74
	v_add_f32_e32 v72, v72, v97
	v_pk_mul_f32 v[100:101], v[2:3], v[2:3]
	v_add_f32_e32 v96, v70, v72
	v_add_f32_e32 v70, v98, v99
	s_waitcnt vmcnt(3)
	v_mov_b32_e32 v92, v77
	s_waitcnt vmcnt(2)
	v_mov_b32_e32 v93, v81
	v_add_f32_e32 v70, v70, v100
	v_mov_b32_e32 v74, v76
	v_mov_b32_e32 v75, v80
	v_pk_mul_f32 v[92:93], v[92:93], v[92:93]
	v_add_f32_e32 v97, v70, v101
	s_waitcnt lgkmcnt(0)
	v_add_f32_e32 v69, v69, v71
	v_mov_b32_e32 v70, v78
	v_mov_b32_e32 v71, v82
	v_pk_fma_f32 v[74:75], v[74:75], v[74:75], v[92:93]
	s_waitcnt vmcnt(1)
	v_mov_b32_e32 v94, v85
	s_waitcnt vmcnt(0)
	v_mov_b32_e32 v95, v89
	v_mov_b32_e32 v72, v79
	v_mov_b32_e32 v73, v83
	v_pk_fma_f32 v[70:71], v[70:71], v[70:71], v[74:75]
	v_mov_b32_e32 v92, v84
	v_mov_b32_e32 v93, v88
	v_pk_mul_f32 v[94:95], v[94:95], v[94:95]
	v_pk_fma_f32 v[70:71], v[72:73], v[72:73], v[70:71]
	v_mov_b32_e32 v72, v86
	v_mov_b32_e32 v73, v90
	v_pk_fma_f32 v[92:93], v[92:93], v[92:93], v[94:95]
	v_mov_b32_e32 v74, v87
	v_mov_b32_e32 v75, v91
	v_pk_fma_f32 v[72:73], v[72:73], v[72:73], v[92:93]
	v_add_f32_e32 v70, v70, v71
	v_pk_fma_f32 v[72:73], v[74:75], v[74:75], v[72:73]
	ds_bpermute_b32 v74, v60, v102
	v_add_f32_e32 v70, v70, v72
	v_add_f32_e32 v70, v70, v73
	ds_bpermute_b32 v71, v60, v70
	ds_bpermute_b32 v98, v64, v69
	s_waitcnt lgkmcnt(2)
	v_add_f32_e32 v74, v102, v74
	ds_bpermute_b32 v75, v61, v74
	v_add_f32_e32 v72, v96, v97
	s_waitcnt lgkmcnt(2)
	v_add_f32_e32 v70, v70, v71
	ds_bpermute_b32 v71, v61, v70
	s_waitcnt lgkmcnt(2)
	v_add_f32_e32 v73, v69, v98
	ds_bpermute_b32 v69, v60, v72
	s_waitcnt lgkmcnt(2)
	v_add_f32_e32 v74, v74, v75
	ds_bpermute_b32 v75, v62, v74
	s_waitcnt lgkmcnt(2)
	v_add_f32_e32 v70, v70, v71
	ds_bpermute_b32 v71, v62, v70
	s_waitcnt lgkmcnt(2)
	v_add_f32_e32 v69, v72, v69
	ds_bpermute_b32 v72, v61, v69
	s_waitcnt lgkmcnt(2)
	v_add_f32_e32 v74, v74, v75
	ds_bpermute_b32 v75, v63, v74
	s_waitcnt lgkmcnt(2)
	v_add_f32_e32 v70, v70, v71
	ds_bpermute_b32 v71, v63, v70
	s_waitcnt lgkmcnt(2)
	v_add_f32_e32 v69, v69, v72
	ds_bpermute_b32 v72, v62, v69
	s_waitcnt lgkmcnt(2)
	v_add_f32_e32 v75, v74, v75
	ds_bpermute_b32 v92, v64, v75
	s_waitcnt lgkmcnt(2)
	v_add_f32_e32 v70, v70, v71
	ds_bpermute_b32 v71, v64, v70
	s_waitcnt lgkmcnt(2)
	v_add_f32_e32 v69, v69, v72
	ds_bpermute_b32 v72, v63, v69
	ds_bpermute_b32 v74, v65, v73
	s_waitcnt lgkmcnt(2)
	v_add_f32_e32 v70, v70, v71
	ds_bpermute_b32 v94, v65, v70
	v_add_f32_e32 v71, v75, v92
	s_waitcnt lgkmcnt(2)
	v_add_f32_e32 v69, v69, v72
	ds_bpermute_b32 v93, v64, v69
	ds_bpermute_b32 v72, v65, v71
	s_waitcnt lgkmcnt(2)
	v_add_f32_e32 v70, v70, v94
	v_fmamk_f32 v70, v70, 0x3a800000, v67
	v_mul_f32_e32 v75, 0x4b800000, v70
	v_cmp_gt_f32_e64 s[8:9], s18, v70
	s_waitcnt lgkmcnt(1)
	v_add_f32_e32 v69, v69, v93
	v_cndmask_b32_e64 v70, v70, v75, s[8:9]
	v_rsq_f32_e32 v75, v70
	ds_bpermute_b32 v70, v65, v69
	v_mul_f32_e32 v92, 0x45800000, v75
	v_cndmask_b32_e64 v92, v75, v92, s[8:9]
	v_pk_mul_f32 v[76:77], v[76:77], v[92:93] op_sel_hi:[1,0]
	v_pk_mul_f32 v[78:79], v[78:79], v[92:93] op_sel_hi:[1,0]
	v_cvt_pk_bf16_f32 v76, v76, v77
	v_cvt_pk_bf16_f32 v77, v78, v79
	global_store_dwordx2 v[58:59], v[76:77], off sc1
	v_pk_mul_f32 v[76:77], v[80:81], v[92:93] op_sel_hi:[1,0]
	v_pk_mul_f32 v[78:79], v[82:83], v[92:93] op_sel_hi:[1,0]
	v_cvt_pk_bf16_f32 v76, v76, v77
	v_cvt_pk_bf16_f32 v77, v78, v79
	global_store_dwordx2 v[58:59], v[76:77], off offset:512 sc1
	v_pk_mul_f32 v[76:77], v[84:85], v[92:93] op_sel_hi:[1,0]
	v_pk_mul_f32 v[78:79], v[86:87], v[92:93] op_sel_hi:[1,0]
	v_cvt_pk_bf16_f32 v76, v76, v77
	v_cvt_pk_bf16_f32 v77, v78, v79
	global_store_dwordx2 v[58:59], v[76:77], off offset:1024 sc1
	v_pk_mul_f32 v[76:77], v[88:89], v[92:93] op_sel_hi:[1,0]
	v_pk_mul_f32 v[78:79], v[90:91], v[92:93] op_sel_hi:[1,0]
	v_cvt_pk_bf16_f32 v76, v76, v77
	v_cvt_pk_bf16_f32 v77, v78, v79
	global_store_dwordx2 v[58:59], v[76:77], off offset:1536 sc1
	s_and_saveexec_b64 s[8:9], s[6:7]
	s_cbranch_execnz .LBB0_1426
	s_or_b64 exec, exec, s[8:9]
	s_and_saveexec_b64 s[6:7], s[0:1]
	s_cbranch_execnz .LBB0_1427

.LBB0_1700:
	v_add_u32_e32 v17, s17, v72
	v_cmp_gt_i32_e64 s[6:7], s16, v17
	v_lshrrev_b32_e32 v83, 3, v72
	v_and_b32_e32 v73, 0x700, v80
	v_cndmask_b32_e64 v16, v72, v17, s[6:7]
	v_lshlrev_b32_e32 v18, 5, v16
	v_lshrrev_b32_e32 v19, 3, v16
	v_and_b32_e32 v18, 0x700, v18
	v_and_b32_e32 v19, 0xf8, v19
	v_and_b32_e32 v20, 0xfffff807, v16
	v_or3_b32 v18, v18, v20, v19
	v_cndmask_b32_e32 v16, v16, v18, vcc
	v_add_u32_e32 v18, s17, v17
	v_cmp_gt_i32_e64 s[4:5], s16, v18
	v_add_u32_e32 v82, s17, v18
	v_cmp_gt_i32_e64 s[0:1], s16, v82
	v_cndmask_b32_e64 v19, v72, v18, s[4:5]
	v_lshlrev_b32_e32 v17, 5, v19
	v_and_b32_e32 v20, 0x700, v17
	v_ashrrev_i32_e32 v17, 31, v16
	v_lshlrev_b64 v[16:17], 12, v[16:17]
	v_lshl_add_u64 v[70:71], v[64:65], 0, v[16:17]
	v_lshrrev_b32_e32 v16, 3, v19
	v_and_b32_e32 v16, 0xf8, v16
	v_and_b32_e32 v17, 0xfffff807, v19
	v_or3_b32 v16, v20, v17, v16
	v_cndmask_b32_e32 v16, v19, v16, vcc
	v_ashrrev_i32_e32 v17, 31, v16
	v_lshlrev_b64 v[16:17], 12, v[16:17]
	global_load_dwordx4 v[60:63], v[70:71], off nt
	global_load_dwordx4 v[56:59], v[70:71], off offset:1024 nt
	v_lshl_add_u64 v[68:69], v[64:65], 0, v[16:17]
	v_cndmask_b32_e64 v16, v72, v82, s[0:1]
	global_load_dwordx4 v[52:55], v[70:71], off offset:2048 nt
	v_lshlrev_b32_e32 v17, 5, v16
	v_lshrrev_b32_e32 v18, 3, v16
	global_load_dwordx4 v[48:51], v[70:71], off offset:3072 nt
	v_and_b32_e32 v19, 0xfffff807, v16
	v_and_b32_e32 v17, 0x700, v17
	v_and_b32_e32 v18, 0xf8, v18
	v_or3_b32 v17, v17, v19, v18
	v_cndmask_b32_e32 v16, v16, v17, vcc
	v_ashrrev_i32_e32 v17, 31, v16
	global_load_dwordx4 v[44:47], v[68:69], off nt
	global_load_dwordx4 v[40:43], v[68:69], off offset:1024 nt
	global_load_dwordx4 v[36:39], v[68:69], off offset:2048 nt
	global_load_dwordx4 v[32:35], v[68:69], off offset:3072 nt
	v_lshlrev_b64 v[16:17], 12, v[16:17]
	v_lshl_add_u64 v[66:67], v[64:65], 0, v[16:17]
	global_load_dwordx4 v[28:31], v[66:67], off nt
	global_load_dwordx4 v[24:27], v[66:67], off offset:1024 nt
	global_load_dwordx4 v[20:23], v[66:67], off offset:2048 nt
	global_load_dwordx4 v[16:19], v[66:67], off offset:3072 nt
	s_waitcnt lgkmcnt(0)
	v_and_b32_e32 v84, 0xfffff807, v72
	v_and_b32_e32 v83, 0xf8, v83
	v_or3_b32 v73, v73, v84, v83
	v_cndmask_b32_e32 v72, v72, v73, vcc
	v_ashrrev_i32_e32 v73, 31, v72
	v_lshlrev_b64 v[72:73], 12, v[72:73]
	v_lshl_add_u64 v[72:73], v[64:65], 0, v[72:73]
	global_load_dwordx4 v[90:93], v[72:73], off nt
	global_load_dwordx4 v[94:97], v[72:73], off offset:1024 nt
	global_load_dwordx4 v[98:101], v[72:73], off offset:2048 nt
	global_load_dwordx4 v[102:105], v[72:73], off offset:3072 nt
	s_waitcnt vmcnt(15)
	v_pk_mul_f32 v[84:85], v[60:61], v[60:61]
	s_waitcnt vmcnt(14)
	v_pk_mul_f32 v[88:89], v[56:57], v[56:57]
	v_pk_mul_f32 v[86:87], v[62:63], v[62:63]
	v_pk_mul_f32 v[106:107], v[58:59], v[58:59]
	s_waitcnt vmcnt(13)
	v_pk_mul_f32 v[108:109], v[52:53], v[52:53]
	v_add_f32_e32 v83, v88, v89
	v_add_f32_e32 v124, v84, v85
	v_pk_mul_f32 v[110:111], v[54:55], v[54:55]
	s_waitcnt vmcnt(12)
	v_pk_mul_f32 v[112:113], v[48:49], v[48:49]
	v_add_f32_e32 v125, v108, v109
	v_add_f32_e32 v83, v83, v106
	v_add_f32_e32 v86, v124, v86
	v_pk_mul_f32 v[114:115], v[50:51], v[50:51]
	v_add_f32_e32 v126, v112, v113
	s_waitcnt vmcnt(11)
	v_pk_mul_f32 v[84:85], v[44:45], v[44:45]
	v_add_f32_e32 v106, v125, v110
	v_add_f32_e32 v83, v83, v107
	v_add_f32_e32 v86, v86, v87
	v_pk_mul_f32 v[88:89], v[46:47], v[46:47]
	s_waitcnt vmcnt(10)
	v_pk_mul_f32 v[108:109], v[40:41], v[40:41]
	v_add_f32_e32 v110, v126, v114
	v_add_f32_e32 v87, v106, v111
	v_add_f32_e32 v83, v86, v83
	v_add_f32_e32 v84, v84, v85
	v_pk_mul_f32 v[112:113], v[42:43], v[42:43]
	s_waitcnt vmcnt(9)
	v_pk_mul_f32 v[116:117], v[36:37], v[36:37]
	v_add_f32_e32 v108, v108, v109
	v_add_f32_e32 v106, v110, v115
	v_add_f32_e32 v83, v83, v87
	v_add_f32_e32 v84, v84, v88
	v_pk_mul_f32 v[118:119], v[38:39], v[38:39]
	v_add_f32_e32 v83, v83, v106
	v_add_f32_e32 v86, v108, v112
	v_add_f32_e32 v84, v84, v89
	v_add_f32_e32 v85, v116, v117
	s_waitcnt vmcnt(6)
	v_pk_mul_f32 v[88:89], v[24:25], v[24:25]
	v_add_f32_e32 v86, v86, v113
	v_add_f32_e32 v85, v85, v118
	v_add_f32_e32 v88, v88, v89
	ds_bpermute_b32 v89, v74, v83
	v_pk_mul_f32 v[120:121], v[32:33], v[32:33]
	v_add_f32_e32 v84, v84, v86
	v_add_f32_e32 v85, v85, v119
	v_pk_mul_f32 v[122:123], v[34:35], v[34:35]
	v_add_f32_e32 v84, v84, v85
	v_add_f32_e32 v85, v120, v121
	v_add_f32_e32 v85, v85, v122
	v_add_f32_e32 v85, v85, v123
	v_add_f32_e32 v116, v84, v85
	v_pk_mul_f32 v[84:85], v[28:29], v[28:29]
	s_waitcnt lgkmcnt(0)
	v_add_f32_e32 v83, v83, v89
	v_add_f32_e32 v84, v84, v85
	ds_bpermute_b32 v85, v75, v83
	v_pk_mul_f32 v[86:87], v[30:31], v[30:31]
	v_pk_mul_f32 v[106:107], v[26:27], v[26:27]
	s_waitcnt vmcnt(5)
	v_pk_mul_f32 v[108:109], v[20:21], v[20:21]
	v_pk_mul_f32 v[110:111], v[22:23], v[22:23]
	s_waitcnt lgkmcnt(0)
	v_add_f32_e32 v83, v83, v85
	v_add_f32_e32 v88, v88, v106
	v_add_f32_e32 v84, v84, v86
	v_add_f32_e32 v86, v108, v109
	ds_bpermute_b32 v85, v76, v83
	v_add_f32_e32 v88, v88, v107
	v_add_f32_e32 v84, v84, v87
	v_add_f32_e32 v86, v86, v110
	s_waitcnt vmcnt(4)
	v_pk_mul_f32 v[112:113], v[16:17], v[16:17]
	v_add_f32_e32 v84, v84, v88
	v_add_f32_e32 v86, v86, v111
	v_pk_mul_f32 v[114:115], v[18:19], v[18:19]
	v_add_f32_e32 v108, v84, v86
	v_add_f32_e32 v84, v112, v113
	v_add_f32_e32 v84, v84, v114
	s_waitcnt vmcnt(3)
	v_mov_b32_e32 v86, v91
	s_waitcnt vmcnt(2)
	v_mov_b32_e32 v87, v95
	v_add_f32_e32 v109, v84, v115
	s_waitcnt lgkmcnt(0)
	v_add_f32_e32 v83, v83, v85
	v_mov_b32_e32 v84, v90
	v_mov_b32_e32 v85, v94
	v_pk_mul_f32 v[86:87], v[86:87], v[86:87]
	v_mov_b32_e32 v88, v93
	v_pk_fma_f32 v[84:85], v[84:85], v[84:85], v[86:87]
	v_mov_b32_e32 v86, v92
	v_mov_b32_e32 v87, v96
	v_mov_b32_e32 v89, v97
	v_pk_fma_f32 v[84:85], v[86:87], v[86:87], v[84:85]
	s_waitcnt vmcnt(1)
	v_mov_b32_e32 v86, v98
	v_pk_fma_f32 v[84:85], v[88:89], v[88:89], v[84:85]
	v_mov_b32_e32 v88, v99
	s_waitcnt vmcnt(0)
	v_mov_b32_e32 v89, v103
	v_mov_b32_e32 v87, v102
	v_pk_mul_f32 v[88:89], v[88:89], v[88:89]
	v_mov_b32_e32 v106, v101
	v_pk_fma_f32 v[86:87], v[86:87], v[86:87], v[88:89]
	v_mov_b32_e32 v88, v100
	v_mov_b32_e32 v89, v104
	v_mov_b32_e32 v107, v105
	v_pk_fma_f32 v[86:87], v[88:89], v[88:89], v[86:87]
	v_add_f32_e32 v84, v84, v85
	v_pk_fma_f32 v[86:87], v[106:107], v[106:107], v[86:87]
	ds_bpermute_b32 v110, v77, v83
	v_add_f32_e32 v84, v84, v86
	v_add_f32_e32 v84, v84, v87
	ds_bpermute_b32 v85, v74, v84
	ds_bpermute_b32 v87, v74, v116
	s_waitcnt lgkmcnt(2)
	v_add_f32_e32 v83, v83, v110
	ds_bpermute_b32 v88, v78, v83
	v_add_f32_e32 v86, v108, v109
	s_waitcnt lgkmcnt(2)
	v_add_f32_e32 v84, v84, v85
	ds_bpermute_b32 v85, v75, v84
	s_waitcnt lgkmcnt(2)
	v_add_f32_e32 v89, v116, v87
	s_waitcnt lgkmcnt(1)
	v_add_f32_e32 v87, v83, v88
	ds_bpermute_b32 v83, v74, v86
	ds_bpermute_b32 v106, v75, v89
	s_waitcnt lgkmcnt(2)
	v_add_f32_e32 v84, v84, v85
	ds_bpermute_b32 v85, v76, v84
	s_waitcnt lgkmcnt(2)
	v_add_f32_e32 v83, v86, v83
	s_waitcnt lgkmcnt(1)
	v_add_f32_e32 v88, v89, v106
	ds_bpermute_b32 v86, v75, v83
	s_waitcnt lgkmcnt(1)
	v_add_f32_e32 v84, v84, v85
	ds_bpermute_b32 v85, v77, v84
	ds_bpermute_b32 v89, v76, v88
	s_waitcnt lgkmcnt(2)
	v_add_f32_e32 v83, v83, v86
	ds_bpermute_b32 v86, v76, v83
	s_waitcnt lgkmcnt(2)
	v_add_f32_e32 v84, v84, v85
	ds_bpermute_b32 v85, v78, v84
	s_waitcnt lgkmcnt(2)
	v_add_f32_e32 v88, v88, v89
	ds_bpermute_b32 v89, v77, v88
	s_waitcnt lgkmcnt(2)
	v_add_f32_e32 v83, v83, v86
	ds_bpermute_b32 v86, v77, v83
	s_waitcnt lgkmcnt(2)
	v_add_f32_e32 v84, v84, v85
	ds_bpermute_b32 v107, v79, v84
	s_waitcnt lgkmcnt(2)
	v_add_f32_e32 v89, v88, v89
	ds_bpermute_b32 v106, v78, v89
	s_waitcnt lgkmcnt(2)
	v_add_f32_e32 v83, v83, v86
	ds_bpermute_b32 v88, v79, v87
	s_waitcnt lgkmcnt(2)
	v_add_f32_e32 v84, v84, v107
	v_fmamk_f32 v84, v84, 0x3a800000, v81
	v_mul_f32_e32 v86, 0x4b800000, v84
	v_cmp_gt_f32_e64 s[2:3], s19, v84
	s_waitcnt lgkmcnt(1)
	v_add_f32_e32 v85, v89, v106
	ds_bpermute_b32 v89, v78, v83
	v_cndmask_b32_e64 v84, v84, v86, s[2:3]
	v_rsq_f32_e32 v106, v84
	ds_bpermute_b32 v86, v79, v85
	s_waitcnt lgkmcnt(1)
	v_add_f32_e32 v83, v83, v89
	v_mul_f32_e32 v89, 0x45800000, v106
	v_cndmask_b32_e64 v106, v106, v89, s[2:3]
	v_pk_mul_f32 v[90:91], v[90:91], v[106:107] op_sel_hi:[1,0]
	v_pk_mul_f32 v[92:93], v[92:93], v[106:107] op_sel_hi:[1,0]
	v_pk_mul_f32 v[90:91], v[0:1], v[90:91]
	v_pk_mul_f32 v[92:93], v[2:3], v[92:93]
	global_store_dwordx4 v[72:73], v[90:93], off sc1
	ds_bpermute_b32 v84, v79, v83
	s_nop 0
	v_pk_mul_f32 v[90:91], v[94:95], v[106:107] op_sel_hi:[1,0]
	v_pk_mul_f32 v[92:93], v[96:97], v[106:107] op_sel_hi:[1,0]
	v_pk_mul_f32 v[90:91], v[4:5], v[90:91]
	v_pk_mul_f32 v[92:93], v[6:7], v[92:93]
	global_store_dwordx4 v[72:73], v[90:93], off offset:1024 sc1
	s_nop 1
	v_pk_mul_f32 v[90:91], v[98:99], v[106:107] op_sel_hi:[1,0]
	v_pk_mul_f32 v[92:93], v[100:101], v[106:107] op_sel_hi:[1,0]
	v_pk_mul_f32 v[90:91], v[8:9], v[90:91]
	v_pk_mul_f32 v[92:93], v[10:11], v[92:93]
	global_store_dwordx4 v[72:73], v[90:93], off offset:2048 sc1
	s_nop 1
	v_pk_mul_f32 v[90:91], v[102:103], v[106:107] op_sel_hi:[1,0]
	v_pk_mul_f32 v[92:93], v[104:105], v[106:107] op_sel_hi:[1,0]
	v_pk_mul_f32 v[90:91], v[12:13], v[90:91]
	v_pk_mul_f32 v[92:93], v[14:15], v[92:93]
	global_store_dwordx4 v[72:73], v[90:93], off offset:3072 sc1
	s_and_saveexec_b64 s[14:15], s[6:7]
	s_cbranch_execnz .LBB0_1703
	s_or_b64 exec, exec, s[14:15]
	s_and_saveexec_b64 s[6:7], s[4:5]
	s_cbranch_execnz .LBB0_1704
